# phase 13 made independent of the grid size (outer loop over wave index); otherwise identical to the rewritten-barrier version
# speedup vs baseline: 1.0014x; 1.0013x over previous
.Lffn_again:
	s_mov_b32 s38, s0
	s_cmpk_gt_u32 s0, 0x7fd
	s_cbranch_scc1 .Lffn_done
	v_readlane_b32 s2, v254, 56
	v_readlane_b32 s3, v254, 57
	s_mul_hi_u32 s34, s0, 0x1745d175
	s_mul_i32 s1, s34, 11
	s_sub_i32 s1, s0, s1
	s_lshl_b32 s1, s1, 8
	s_load_dwordx2 s[30:31], s[2:3], 0x108
	s_load_dwordx4 s[24:27], s[2:3], 0xe0
	s_load_dwordx2 s[28:29], s[2:3], 0x30
	s_load_dwordx2 s[22:23], s[2:3], 0x100
	v_and_b32_e32 v2, 63, v174
	v_lshl_add_u32 v2, v2, 2, s1
	v_lshlrev_b32_e32 v28, 1, v2
	v_add_u32_e32 v29, 0x1600, v28
	v_lshlrev_b32_e32 v30, 2, v2
	v_add_u32_e32 v31, 0x2c00, v30
	v_mov_b32_e32 v160, 0xbfb8aa3b
	v_mov_b32_e32 v161, 0xbfb8aa3b
	v_mov_b32_e32 v162, 1.0
	v_mov_b32_e32 v163, 1.0
	s_cmpk_lt_u32 s34, 0x5e
	s_cselect_b32 s35, 6, 5
	s_mul_i32 s37, s35, 0xba
	s_add_i32 s37, s37, s34
	s_sub_i32 s37, s37, 0x400
	s_cmpk_lt_u32 s34, 0x24
	s_cselect_b32 s36, 1, 0
	s_cmpk_gt_u32 s34, 0x5d
	s_cselect_b32 s1, 1, 0
	s_or_b32 s36, s36, s1
	s_waitcnt lgkmcnt(0)
	global_load_dwordx4 v[32:35], v30, s[24:25]
	global_load_dwordx4 v[48:51], v31, s[24:25]
	s_add_u32 s4, s24, 0x5800
	s_addc_u32 s5, s25, 0
	global_load_dwordx4 v[36:39], v30, s[4:5]
	global_load_dwordx4 v[52:55], v31, s[4:5]
	s_add_u32 s4, s4, 0x5800
	s_addc_u32 s5, s5, 0
	global_load_dwordx4 v[40:43], v30, s[4:5]
	global_load_dwordx4 v[56:59], v31, s[4:5]
	global_load_dwordx4 v[44:47], v30, s[26:27]
	global_load_dwordx4 v[60:63], v31, s[26:27]
	s_cmp_eq_u32 s36, 0
	s_cbranch_scc1 .Lffn_nosld
	s_mul_i32 s0, s37, 0xb000
	s_add_u32 s4, s28, s0
	s_addc_u32 s5, s29, 0
	global_load_dwordx4 v[178:181], v30, s[4:5]
	global_load_dwordx4 v[182:185], v31, s[4:5]
	s_add_u32 s4, s4, 0x5800
	s_addc_u32 s5, s5, 0
	global_load_dwordx4 v[186:189], v30, s[4:5]
	global_load_dwordx4 v[190:193], v31, s[4:5]
	s_add_u32 s4, s30, 0x9408000
	s_addc_u32 s5, s31, 0
	s_add_u32 s4, s4, 0xb000000
	s_addc_u32 s5, s5, 0
	s_add_u32 s4, s4, s0
	s_addc_u32 s5, s5, 0
	global_load_dwordx2 v[194:195], v28, s[4:5] nt
	global_load_dwordx2 v[196:197], v29, s[4:5] nt
	s_add_u32 s4, s4, 0x2c00
	s_addc_u32 s5, s5, 0
	global_load_dwordx2 v[198:199], v28, s[4:5] nt
	global_load_dwordx2 v[200:201], v29, s[4:5] nt
	s_add_u32 s4, s4, 0x2c00
	s_addc_u32 s5, s5, 0
	global_load_dwordx2 v[202:203], v28, s[4:5] nt
	global_load_dwordx2 v[204:205], v29, s[4:5] nt
	s_add_u32 s4, s4, 0x2c00
	s_addc_u32 s5, s5, 0
	global_load_dwordx2 v[206:207], v28, s[4:5] nt
	global_load_dwordx2 v[208:209], v29, s[4:5] nt

.Lffn_next:
	v_readlane_b32 s0, v254, 62
	s_lshl_b32 s0, s0, 3
	s_add_i32 s0, s38, s0
	s_branch .Lffn_again
